# start skew refined: w_in 7 offsets of 32 workgroups, mlp_in 4 offsets for the 8-tile workgroups (smaller simultaneous store bursts)
# baseline (speedup 1.0000x reference)
; #define PG8_STAGE(bufoff, gbase, voff) do { _Pragma("unroll") for (int _i = 0; _i < 2; ++_i) \
;         __builtin_amdgcn_global_load_lds((const unsigned*)((const char*)(gbase) + (voff)[_i]), (LAS unsigned*)(lds + (bufoff) + ldsw + _i * 8192), 16, 0, 0); } while (0)
; #define PG8_WAIT_V(n) asm volatile("s_waitcnt vmcnt(" #n ")" ::: "memory")
; #define PG8_BAR __builtin_amdgcn_s_barrier()
; #define PG8_PTRS(u, pa, pb) do { const size_t _ko = (u).ks >= 0 ? (size_t)(u).ks * (size_t)(K / KSPLIT) * 2 : 0; \
;         const char* _a = (const char*)g.A + (size_t)(u).pm * tstep + _ko; const char* _b = (const char*)g.Bt + (size_t)(u).pn * tstep + _ko; \
;         if ((u).pn >= g.nN_main) { pa = _b; pb = _a; } else { pa = _a; pb = _b; } } while (0)
; template <class EpiT, bool ALIGN_EPI>
; __device__ __forceinline__ void gemm_phase(LAS unsigned char* lds, const Gemm g, const StaticOrder& S, const EpiT& E, const int tid) {
;     ...
;     Unit cur, nxt; int ui = 0;
;     if (!S.next(0, cur)) return;
;     f32x4 acc[2][2][4][2];
; #pragma unroll
;     for (int a = 0; a < 2; ++a)
; #pragma unroll
;         for (int b = 0; b < 2; ++b)
; #pragma unroll
;             for (int m = 0; m < 4; ++m)
; #pragma unroll
;                 for (int n = 0; n < 2; ++n) acc[a][b][m][n] = (f32x4){0.f, 0.f, 0.f, 0.f};
;     bf16x8 At[4][2], B0[2][2], B1[2][2];
;     const char* cA; const char* cB; PG8_PTRS(cur, cA, cB);
;     PG8_STAGE(PG8_SB(0, 0), cB, voffB); PG8_STAGE(PG8_SB(0, 1), cB + hstep, voffB); PG8_STAGE(PG8_SA(0, 0), cA, voffA); PG8_STAGE(PG8_SA(0, 1), cA + hstep, voffA);
;     if (wr == 1) PG8_BAR;
;     PG8_WAIT_V(2); PG8_BAR;
;     PG8_STAGE(PG8_SB(1, 0), cB + kstep, voffB); PG8_STAGE(PG8_SA(1, 0), cA + kstep, voffA); PG8_STAGE(PG8_SB(1, 1), cB + hstep + kstep, voffB);
;     PG8_WAIT_V(6); PG8_BAR;
; __global__ void __launch_bounds__(NTHR) fwd_kernel(Params p) {
;     ...
;                 pg8::Gemm g{XN, (const bf16_t*)(q.ws + WS_W1) + (size_t)l * FF * DM, DM, 1 << 30};
;                 pg8::StaticOrder S; S.init(nMrows, 16, G, (int)blockIdx.x);
;                 pg8::Epi<2> E{(bf16_t*)(q.ws + WS_H), nullptr, nullptr};
;                 pg8::gemm_phase<pg8::Epi<2>, true>(lds, g, S, E, tid);
.LBB0_171:
	s_and_b64 vcc, exec, s[0:1]
	s_cbranch_vccz .LBB0_190
	s_lshl_b32 s30, s97, 4
	s_cmp_ge_i32 s2, s30
	v_readfirstlane_b32 s1, v166
	s_cbranch_scc1 .LBB0_190
	s_cmp_eq_u32 s97, 0x88
	s_cbranch_scc0 .Lskew_done_mi
	s_bitcmp1_b32 s2, 7
	s_cbranch_scc0 .Lskew_done_mi
	s_lshr_b32 s32, s2, 5
	s_sub_i32 s32, s32, 3
.Lskew_loop_mi:
	s_sleep 127
	s_sleep 64
	s_add_i32 s32, s32, -1
	s_cmp_lg_u32 s32, 0
	s_cbranch_scc1 .Lskew_loop_mi

; __global__ void __launch_bounds__(NTHR) fwd_kernel(Params p) {
;     ...
;                 pg8::Gemm g{XN, (const bf16_t*)(q.ws + WS_WIN) + (size_t)l * NIN * DM, DM, 6};
;                 pg8::StaticOrder S; S.init(MT / 256, 8, G, (int)blockIdx.x);
;                 pg8::Epi<0> E{(bf16_t*)(q.ws + WS_PB), (bf16_t*)(q.ws + WS_VT), nullptr};
;                 pg8::gemm_phase<pg8::Epi<0>, true>(lds, g, S, E, tid);
.LBB0_340:
	s_andn2_b64 vcc, exec, s[50:51]
	s_cbranch_vccnz .LBB0_362
	v_readlane_b32 s0, v253, 16
	v_readlane_b32 s1, v253, 17
	s_andn2_b64 vcc, exec, s[0:1]
	v_readfirstlane_b32 s0, v166
	s_cbranch_vccnz .LBB0_362
	s_lshr_b32 s32, s2, 5
	s_sub_i32 s32, s32, 1
	s_max_i32 s32, s32, 0
	s_cmp_eq_u32 s32, 0
	s_cbranch_scc1 .Lskew_done_win
